# w_in GEMM k-loop: LDS fragment reads via one invariant base + immediate offsets and LDS-DMA in scalar-base form (32 fewer VALU per k-iteration in load segments)
# speedup vs baseline: 1.0068x; 1.0068x over previous
.LBB0_317:
	v_readlane_b32 s24, v254, 56
	s_lshl_b32 s6, s24, 1
	s_ashr_i32 s7, s6, 31
	s_lshl_b64 s[6:7], s[6:7], 16
	v_readlane_b32 s8, v254, 54
	v_readlane_b32 s9, v254, 55
	s_add_u32 s14, s8, s6
	s_addc_u32 s15, s9, s7
	s_add_u32 s44, s94, 0x100000
	s_addc_u32 s45, s95, 0
	s_add_i32 s46, s36, 0x18000
	s_and_b32 s21, s1, 3
	v_lshl_add_u64 v[6:7], v[6:7], 0, s[98:99]
	s_mov_b32 m0, s46
	s_add_i32 s47, s36, 0x1a000
	s_lshl_b32 s8, s20, 13
	s_lshl_b32 s22, s21, 5
	s_lshl_b32 s9, s21, 12
	s_waitcnt vmcnt(2)
	s_barrier
	global_load_lds_dwordx4 v[6:7], off
	v_lshl_add_u64 v[4:5], v[4:5], 0, s[98:99]
	s_mov_b32 m0, s47
	s_add_i32 s48, s36, 0x8000
	s_add_i32 s49, s36, 0xa000
	global_load_lds_dwordx4 v[4:5], off
	v_lshl_add_u64 v[0:1], v[0:1], 0, s[98:99]
	s_mov_b32 m0, s48
	s_add_u32 s6, s28, 0x80080
	global_load_lds_dwordx4 v[0:1], off
	v_lshl_add_u64 v[0:1], v[2:3], 0, s[98:99]
	s_mov_b32 m0, s49
	s_addc_u32 s7, s29, 0
	s_add_i32 s50, s36, 0x1c000
	global_load_lds_dwordx4 v[0:1], off
	v_lshl_add_u64 v[0:1], s[6:7], 0, v[64:65]
	s_mov_b32 m0, s50
	s_add_i32 s51, s36, 0x1e000
	global_load_lds_dwordx4 v[0:1], off
	v_lshl_add_u64 v[0:1], s[6:7], 0, v[146:147]
	s_mov_b32 m0, s51
	v_bfe_u32 v3, v194, 4, 2
	global_load_lds_dwordx4 v[0:1], off
	v_and_b32_e32 v1, 15, v194
	v_lshlrev_b32_e32 v2, 4, v3
	v_lshlrev_b32_e32 v4, 2, v194
	s_cmpk_lt_u32 s0, 0x100
	v_lshl_or_b32 v2, v1, 6, v2
	v_and_b32_e32 v4, 32, v4
	s_cselect_b64 s[16:17], -1, 0
	s_and_b32 s0, s0, 0xc0
	v_lshl_or_b32 v178, s20, 6, v1
	v_bitop3_b32 v179, v2, s8, v4 bitop3:0xde
	v_bitop3_b32 v180, s9, v2, v4 bitop3:0xf6
	v_cmp_eq_u32_e64 s[8:9], 0, v1
	v_or_b32_e32 v1, s0, v240
	v_mov_b32_e32 v2, s0
	s_movk_i32 s0, 0x7f
	v_bitop3_b32 v2, v240, s0, v2 bitop3:0xc8
	s_lshl_b32 s0, s21, 2
	s_lshl_b32 s20, s20, 10
	s_or_b32 s54, s0, 0x20400
	s_lshl_b32 s0, s21, 7
	s_or_b32 s0, s20, s0
	s_add_i32 s0, s0, 0x22400
	v_lshlrev_b32_e32 v0, 3, v3
	v_cmp_eq_u32_e64 s[6:7], 0, v3
	v_lshl_or_b32 v189, v3, 5, s0
	v_mov_b32_e32 v3, 0x22400
	v_lshl_or_b32 v190, v1, 2, v3
	v_lshlrev_b32_e32 v1, 15, v12
	v_and_b32_e32 v1, 0xffff0000, v1
	v_lshl_add_u32 v1, v11, 12, v1
	v_and_b32_e32 v3, 1, v12
	v_lshl_or_b32 v1, v3, 6, v1
	v_lshl_add_u32 v152, v13, 1, v1
	v_lshlrev_b32_e32 v1, 15, v8
	v_and_b32_e32 v1, 0xffff0000, v1
	s_waitcnt vmcnt(6)
	v_or_b32_e32 v182, 16, v178
	v_or_b32_e32 v183, 32, v178
	v_or_b32_e32 v184, 48, v178
	v_add_u32_e32 v185, 0x80, v178
	v_add_u32_e32 v186, 0x90, v178
	v_add_u32_e32 v187, 0xa0, v178
	v_add_u32_e32 v188, 0xb0, v178
	v_lshl_add_u32 v1, v9, 12, v1
	v_and_b32_e32 v3, 1, v8
	v_lshlrev_b32_e32 v4, 5, v182
	v_lshlrev_b32_e32 v5, 5, v183
	v_lshlrev_b32_e32 v6, 5, v184
	v_lshlrev_b32_e32 v7, 5, v185
	v_lshlrev_b32_e32 v14, 5, v186
	v_lshlrev_b32_e32 v15, 5, v187
	v_lshlrev_b32_e32 v16, 5, v188
	s_lshr_b32 s53, s1, 1
	v_lshl_or_b32 v1, v3, 6, v1
	v_readlane_b32 s0, v254, 35
	s_mov_b32 s52, 0
	v_lshlrev_b32_e32 v181, 5, v178
	s_mul_hi_i32 s55, s24, 0x1800
	s_mul_i32 s78, s24, 0x1800
	v_or_b32_e32 v191, s22, v0
	v_mov_b32_e32 v153, v65
	v_lshl_add_u32 v154, v10, 1, v1
	v_mov_b32_e32 v155, v65
	s_lshl_b32 s79, s22, 2
	v_lshlrev_b32_e32 v192, 2, v0
	v_add_u32_e32 v193, 0x20400, v4
	v_add_u32_e32 v195, 0x20400, v5
	v_add_u32_e32 v196, 0x20400, v6
	v_add_u32_e32 v197, 0x20400, v7
	v_add_u32_e32 v198, 0x20400, v14
	v_add_u32_e32 v199, 0x20400, v15
	v_add_u32_e32 v200, 0x20400, v16
	v_lshlrev_b32_e32 v201, 2, v2
	v_readlane_b32 s88, v254, 23
	s_mov_b32 s87, s0
	v_readlane_b32 s25, v254, 57
	s_barrier
	v_readlane_b32 s1, v254, 36
	v_add_u32_e32 v241, 0x10000, v180
	s_branch .LBB0_320

.LBB0_322:
	s_ashr_i32 s1, s0, 31
	s_lshl_b64 s[24:25], s[0:1], 20
	s_add_u32 s24, s80, s24
	s_addc_u32 s25, s81, s25
	s_and_b64 s[26:27], s[22:23], exec
	s_cselect_b32 s1, s25, s11
	s_cselect_b32 s34, s24, s10
	s_ashr_i32 s21, s20, 31
	s_lshl_b64 s[26:27], s[20:21], 20
	s_add_u32 s26, s2, s26
	s_addc_u32 s27, s5, s27
	s_and_b64 s[30:31], s[22:23], exec
	s_cselect_b32 s21, s27, s29
	s_cselect_b32 s35, s26, s28
	s_add_u32 s10, s10, 0x80080
	s_addc_u32 s11, s11, 0
	s_add_u32 s72, s28, 0x100
	v_mov_b32_e32 v0, 0
	s_addc_u32 s73, s29, 0
	s_mov_b32 s74, -2
	s_waitcnt lgkmcnt(0)
	v_mov_b32_e32 v1, v0
	v_mov_b32_e32 v2, v0
	v_mov_b32_e32 v3, v0
	v_mov_b32_e32 v4, v0
	v_mov_b32_e32 v5, v0
	v_mov_b32_e32 v6, v0
	v_mov_b32_e32 v7, v0
	v_mov_b32_e32 v16, v0
	v_mov_b32_e32 v17, v0
	v_mov_b32_e32 v18, v0
	v_mov_b32_e32 v19, v0
	v_mov_b32_e32 v20, v0
	v_mov_b32_e32 v21, v0
	v_mov_b32_e32 v22, v0
	v_mov_b32_e32 v23, v0
	v_mov_b32_e32 v32, v0
	v_mov_b32_e32 v33, v0
	v_mov_b32_e32 v34, v0
	v_mov_b32_e32 v35, v0
	v_mov_b32_e32 v36, v0
	v_mov_b32_e32 v37, v0
	v_mov_b32_e32 v38, v0
	v_mov_b32_e32 v39, v0
	v_mov_b32_e32 v48, v0
	v_mov_b32_e32 v49, v0
	v_mov_b32_e32 v50, v0
	v_mov_b32_e32 v51, v0
	v_mov_b32_e32 v52, v0
	v_mov_b32_e32 v53, v0
	v_mov_b32_e32 v54, v0
	v_mov_b32_e32 v55, v0
	v_mov_b32_e32 v8, v0
	v_mov_b32_e32 v9, v0
	v_mov_b32_e32 v10, v0
	v_mov_b32_e32 v11, v0
	v_mov_b32_e32 v12, v0
	v_mov_b32_e32 v13, v0
	v_mov_b32_e32 v14, v0
	v_mov_b32_e32 v15, v0
	v_mov_b32_e32 v24, v0
	v_mov_b32_e32 v25, v0
	v_mov_b32_e32 v26, v0
	v_mov_b32_e32 v27, v0
	v_mov_b32_e32 v28, v0
	v_mov_b32_e32 v29, v0
	v_mov_b32_e32 v30, v0
	v_mov_b32_e32 v31, v0
	v_mov_b32_e32 v40, v0
	v_mov_b32_e32 v41, v0
	v_mov_b32_e32 v42, v0
	v_mov_b32_e32 v43, v0
	v_mov_b32_e32 v44, v0
	v_mov_b32_e32 v45, v0
	v_mov_b32_e32 v46, v0
	v_mov_b32_e32 v47, v0
	v_mov_b32_e32 v56, v0
	v_mov_b32_e32 v57, v0
	v_mov_b32_e32 v58, v0
	v_mov_b32_e32 v59, v0
	v_mov_b32_e32 v60, v0
	v_mov_b32_e32 v61, v0
	v_mov_b32_e32 v62, v0
	v_mov_b32_e32 v63, v0
	v_mov_b32_e32 v66, v0
	v_mov_b32_e32 v67, v0
	v_mov_b32_e32 v68, v0
	v_mov_b32_e32 v69, v0
	v_mov_b32_e32 v70, v0
	v_mov_b32_e32 v71, v0
	v_mov_b32_e32 v72, v0
	v_mov_b32_e32 v73, v0
	v_mov_b32_e32 v82, v0
	v_mov_b32_e32 v83, v0
	v_mov_b32_e32 v84, v0
	v_mov_b32_e32 v85, v0
	v_mov_b32_e32 v86, v0
	v_mov_b32_e32 v87, v0
	v_mov_b32_e32 v88, v0
	v_mov_b32_e32 v89, v0
	v_mov_b32_e32 v98, v0
	v_mov_b32_e32 v99, v0
	v_mov_b32_e32 v100, v0
	v_mov_b32_e32 v101, v0
	v_mov_b32_e32 v102, v0
	v_mov_b32_e32 v103, v0
	v_mov_b32_e32 v104, v0
	v_mov_b32_e32 v105, v0
	s_waitcnt vmcnt(0)
	v_mov_b32_e32 v114, v0
	v_mov_b32_e32 v115, v0
	v_mov_b32_e32 v116, v0
	v_mov_b32_e32 v117, v0
	v_mov_b32_e32 v118, v0
	v_mov_b32_e32 v119, v0
	v_mov_b32_e32 v120, v0
	v_mov_b32_e32 v121, v0
	v_mov_b32_e32 v74, v0
	v_mov_b32_e32 v75, v0
	v_mov_b32_e32 v76, v0
	v_mov_b32_e32 v77, v0
	v_mov_b32_e32 v78, v0
	v_mov_b32_e32 v79, v0
	v_mov_b32_e32 v80, v0
	v_mov_b32_e32 v81, v0
	v_mov_b32_e32 v90, v0
	v_mov_b32_e32 v91, v0
	v_mov_b32_e32 v92, v0
	v_mov_b32_e32 v93, v0
	v_mov_b32_e32 v94, v0
	v_mov_b32_e32 v95, v0
	v_mov_b32_e32 v96, v0
	v_mov_b32_e32 v97, v0
	v_mov_b32_e32 v106, v0
	v_mov_b32_e32 v107, v0
	v_mov_b32_e32 v108, v0
	v_mov_b32_e32 v109, v0
	v_mov_b32_e32 v110, v0
	v_mov_b32_e32 v111, v0
	v_mov_b32_e32 v112, v0
	v_mov_b32_e32 v113, v0
	v_mov_b32_e32 v122, v0
	v_mov_b32_e32 v123, v0
	v_mov_b32_e32 v124, v0
	v_mov_b32_e32 v125, v0
	v_mov_b32_e32 v126, v0
	v_mov_b32_e32 v127, v0
	v_mov_b32_e32 v128, v0
	v_mov_b32_e32 v129, v0
.LBB0_323:
	ds_read_b128 v[130:133], v241
	ds_read_b128 v[134:137], v241 offset:1024
	ds_read_b128 v[138:141], v241 offset:2048
	ds_read_b128 v[142:145], v241 offset:3072
	ds_read_b128 v[156:159], v241 offset:16384
	ds_read_b128 v[160:163], v241 offset:17408
	ds_read_b128 v[164:167], v241 offset:18432
	ds_read_b128 v[168:171], v241 offset:19456
	s_add_u32 s28, s10, 0xfff80080
	s_addc_u32 s29, s11, -1
	s_cmp_eq_u32 s74, 28
	s_cselect_b32 s31, s1, s29
	s_cselect_b32 s30, s34, s28
	s_cselect_b32 s29, s21, s73
	s_cselect_b32 s28, s35, s72
	s_add_i32 m0, s36, 0xc000
	ds_read_b128 v[172:175], v179
	ds_read_b128 v[202:205], v179 offset:1024
	ds_read_b128 v[206:209], v179 offset:2048
	ds_read_b128 v[210:213], v179 offset:3072
	ds_read_b128 v[214:217], v179 offset:4096
	ds_read_b128 v[218:221], v179 offset:5120
	ds_read_b128 v[222:225], v179 offset:6144
	ds_read_b128 v[242:245], v179 offset:7168
	global_load_lds_dwordx4 v152, s[10:11]
	s_add_i32 m0, s36, 0xe000
	s_nop 0
	global_load_lds_dwordx4 v154, s[10:11]
	s_waitcnt vmcnt(8)
	s_waitcnt lgkmcnt(0)
	s_barrier
	s_setprio 1
	s_waitcnt lgkmcnt(0)
	v_mfma_f32_16x16x32_bf16 v[126:129], v[130:133], v[172:175], v[126:129]
	v_mfma_f32_16x16x32_bf16 v[122:125], v[138:141], v[172:175], v[122:125]
	v_mfma_f32_16x16x32_bf16 v[110:113], v[130:133], v[206:209], v[110:113]
	v_mfma_f32_16x16x32_bf16 v[106:109], v[138:141], v[206:209], v[106:109]
	v_mfma_f32_16x16x32_bf16 v[94:97], v[130:133], v[214:217], v[94:97]
	v_mfma_f32_16x16x32_bf16 v[90:93], v[138:141], v[214:217], v[90:93]
	v_mfma_f32_16x16x32_bf16 v[78:81], v[130:133], v[222:225], v[78:81]
	v_mfma_f32_16x16x32_bf16 v[74:77], v[138:141], v[222:225], v[74:77]
	v_mfma_f32_16x16x32_bf16 v[126:129], v[134:137], v[202:205], v[126:129]
	v_mfma_f32_16x16x32_bf16 v[122:125], v[142:145], v[202:205], v[122:125]
	v_mfma_f32_16x16x32_bf16 v[110:113], v[134:137], v[210:213], v[110:113]
	v_mfma_f32_16x16x32_bf16 v[106:109], v[142:145], v[210:213], v[106:109]
	v_mfma_f32_16x16x32_bf16 v[94:97], v[134:137], v[218:221], v[94:97]
	v_mfma_f32_16x16x32_bf16 v[90:93], v[142:145], v[218:221], v[90:93]
	v_mfma_f32_16x16x32_bf16 v[78:81], v[134:137], v[242:245], v[78:81]
	v_mfma_f32_16x16x32_bf16 v[74:77], v[142:145], v[242:245], v[74:77]
	s_setprio 0
	s_setprio 1
	v_mfma_f32_16x16x32_bf16 v[118:121], v[156:159], v[172:175], v[118:121]
	v_mfma_f32_16x16x32_bf16 v[114:117], v[164:167], v[172:175], v[114:117]
	v_mfma_f32_16x16x32_bf16 v[102:105], v[156:159], v[206:209], v[102:105]
	v_mfma_f32_16x16x32_bf16 v[98:101], v[164:167], v[206:209], v[98:101]
	v_mfma_f32_16x16x32_bf16 v[86:89], v[156:159], v[214:217], v[86:89]
	v_mfma_f32_16x16x32_bf16 v[82:85], v[164:167], v[214:217], v[82:85]
	v_mfma_f32_16x16x32_bf16 v[70:73], v[156:159], v[222:225], v[70:73]
	v_mfma_f32_16x16x32_bf16 v[66:69], v[164:167], v[222:225], v[66:69]
	v_mfma_f32_16x16x32_bf16 v[118:121], v[160:163], v[202:205], v[118:121]
	v_mfma_f32_16x16x32_bf16 v[114:117], v[168:171], v[202:205], v[114:117]
	v_mfma_f32_16x16x32_bf16 v[102:105], v[160:163], v[210:213], v[102:105]
	v_mfma_f32_16x16x32_bf16 v[98:101], v[168:171], v[210:213], v[98:101]
	v_mfma_f32_16x16x32_bf16 v[86:89], v[160:163], v[218:221], v[86:89]
	v_mfma_f32_16x16x32_bf16 v[82:85], v[168:171], v[218:221], v[82:85]
	v_mfma_f32_16x16x32_bf16 v[70:73], v[160:163], v[242:245], v[70:73]
	v_mfma_f32_16x16x32_bf16 v[66:69], v[168:171], v[242:245], v[66:69]
	s_setprio 0
	s_barrier
	s_mov_b32 m0, s37
	s_add_u32 s76, s28, 0x80000
	ds_read_b128 v[172:175], v179 offset:16384
	ds_read_b128 v[202:205], v179 offset:17408
	ds_read_b128 v[206:209], v179 offset:18432
	ds_read_b128 v[210:213], v179 offset:19456
	ds_read_b128 v[214:217], v179 offset:20480
	ds_read_b128 v[218:221], v179 offset:21504
	ds_read_b128 v[222:225], v179 offset:22528
	ds_read_b128 v[242:245], v179 offset:23552
	global_load_lds_dwordx4 v64, s[28:29]
	s_mov_b32 m0, s38
	s_addc_u32 s77, s29, 0
	global_load_lds_dwordx4 v146, s[28:29]
	s_mov_b32 m0, s39
	s_nop 0
	global_load_lds_dwordx4 v64, s[76:77]
	s_mov_b32 m0, s40
	s_nop 0
	global_load_lds_dwordx4 v146, s[76:77]
	s_mov_b32 m0, s36
	s_nop 0
	global_load_lds_dwordx4 v150, s[30:31]
	s_mov_b32 m0, s41
	s_nop 0
	global_load_lds_dwordx4 v148, s[30:31]
	s_waitcnt vmcnt(8)
	s_waitcnt lgkmcnt(0)
	s_barrier
	s_setprio 1
	s_waitcnt lgkmcnt(0)
	v_mfma_f32_16x16x32_bf16 v[60:63], v[130:133], v[172:175], v[60:63]
	v_mfma_f32_16x16x32_bf16 v[56:59], v[138:141], v[172:175], v[56:59]
	v_mfma_f32_16x16x32_bf16 v[44:47], v[130:133], v[206:209], v[44:47]
	v_mfma_f32_16x16x32_bf16 v[40:43], v[138:141], v[206:209], v[40:43]
	v_mfma_f32_16x16x32_bf16 v[28:31], v[130:133], v[214:217], v[28:31]
	v_mfma_f32_16x16x32_bf16 v[24:27], v[138:141], v[214:217], v[24:27]
	v_mfma_f32_16x16x32_bf16 v[12:15], v[130:133], v[222:225], v[12:15]
	v_mfma_f32_16x16x32_bf16 v[8:11], v[138:141], v[222:225], v[8:11]
	v_mfma_f32_16x16x32_bf16 v[60:63], v[134:137], v[202:205], v[60:63]
	v_mfma_f32_16x16x32_bf16 v[56:59], v[142:145], v[202:205], v[56:59]
	v_mfma_f32_16x16x32_bf16 v[44:47], v[134:137], v[210:213], v[44:47]
	v_mfma_f32_16x16x32_bf16 v[40:43], v[142:145], v[210:213], v[40:43]
	v_mfma_f32_16x16x32_bf16 v[28:31], v[134:137], v[218:221], v[28:31]
	v_mfma_f32_16x16x32_bf16 v[24:27], v[142:145], v[218:221], v[24:27]
	v_mfma_f32_16x16x32_bf16 v[12:15], v[134:137], v[242:245], v[12:15]
	v_mfma_f32_16x16x32_bf16 v[8:11], v[142:145], v[242:245], v[8:11]
	s_setprio 0
	s_setprio 1
	v_mfma_f32_16x16x32_bf16 v[52:55], v[156:159], v[172:175], v[52:55]
	v_mfma_f32_16x16x32_bf16 v[48:51], v[164:167], v[172:175], v[48:51]
	v_mfma_f32_16x16x32_bf16 v[36:39], v[156:159], v[206:209], v[36:39]
	v_mfma_f32_16x16x32_bf16 v[32:35], v[164:167], v[206:209], v[32:35]
	v_mfma_f32_16x16x32_bf16 v[20:23], v[156:159], v[214:217], v[20:23]
	v_mfma_f32_16x16x32_bf16 v[16:19], v[164:167], v[214:217], v[16:19]
	v_mfma_f32_16x16x32_bf16 v[4:7], v[156:159], v[222:225], v[4:7]
	v_mfma_f32_16x16x32_bf16 v[0:3], v[164:167], v[222:225], v[0:3]
	v_mfma_f32_16x16x32_bf16 v[52:55], v[160:163], v[202:205], v[52:55]
	v_mfma_f32_16x16x32_bf16 v[48:51], v[168:171], v[202:205], v[48:51]
	v_mfma_f32_16x16x32_bf16 v[36:39], v[160:163], v[210:213], v[36:39]
	v_mfma_f32_16x16x32_bf16 v[32:35], v[168:171], v[210:213], v[32:35]
	v_mfma_f32_16x16x32_bf16 v[20:23], v[160:163], v[218:221], v[20:23]
	v_mfma_f32_16x16x32_bf16 v[16:19], v[168:171], v[218:221], v[16:19]
	v_mfma_f32_16x16x32_bf16 v[4:7], v[160:163], v[242:245], v[4:7]
	v_mfma_f32_16x16x32_bf16 v[0:3], v[168:171], v[242:245], v[0:3]
	s_setprio 0
	s_barrier
	ds_read_b128 v[130:133], v241 offset:32768
	ds_read_b128 v[134:137], v241 offset:33792
	ds_read_b128 v[138:141], v241 offset:34816
	ds_read_b128 v[142:145], v241 offset:35840
	ds_read_b128 v[156:159], v241 offset:49152
	ds_read_b128 v[160:163], v241 offset:50176
	ds_read_b128 v[164:167], v241 offset:51200
	ds_read_b128 v[168:171], v241 offset:52224
	s_add_u32 s56, s30, 0x80000
	s_addc_u32 s57, s31, 0
	s_mov_b32 m0, s42
	ds_read_b128 v[172:175], v179 offset:32768
	ds_read_b128 v[202:205], v179 offset:33792
	ds_read_b128 v[206:209], v179 offset:34816
	ds_read_b128 v[210:213], v179 offset:35840
	ds_read_b128 v[214:217], v179 offset:36864
	ds_read_b128 v[218:221], v179 offset:37888
	ds_read_b128 v[222:225], v179 offset:38912
	ds_read_b128 v[242:245], v179 offset:39936
	global_load_lds_dwordx4 v150, s[56:57]
	s_mov_b32 m0, s43
	s_nop 0
	global_load_lds_dwordx4 v148, s[56:57]
	s_waitcnt vmcnt(8)
	s_waitcnt lgkmcnt(0)
	s_barrier
	s_setprio 1
	s_waitcnt lgkmcnt(0)
	v_mfma_f32_16x16x32_bf16 v[126:129], v[130:133], v[172:175], v[126:129]
	v_mfma_f32_16x16x32_bf16 v[122:125], v[138:141], v[172:175], v[122:125]
	v_mfma_f32_16x16x32_bf16 v[110:113], v[130:133], v[206:209], v[110:113]
	v_mfma_f32_16x16x32_bf16 v[106:109], v[138:141], v[206:209], v[106:109]
	v_mfma_f32_16x16x32_bf16 v[94:97], v[130:133], v[214:217], v[94:97]
	v_mfma_f32_16x16x32_bf16 v[90:93], v[138:141], v[214:217], v[90:93]
	v_mfma_f32_16x16x32_bf16 v[78:81], v[130:133], v[222:225], v[78:81]
	v_mfma_f32_16x16x32_bf16 v[74:77], v[138:141], v[222:225], v[74:77]
	v_mfma_f32_16x16x32_bf16 v[126:129], v[134:137], v[202:205], v[126:129]
	v_mfma_f32_16x16x32_bf16 v[122:125], v[142:145], v[202:205], v[122:125]
	v_mfma_f32_16x16x32_bf16 v[110:113], v[134:137], v[210:213], v[110:113]
	v_mfma_f32_16x16x32_bf16 v[106:109], v[142:145], v[210:213], v[106:109]
	v_mfma_f32_16x16x32_bf16 v[94:97], v[134:137], v[218:221], v[94:97]
	v_mfma_f32_16x16x32_bf16 v[90:93], v[142:145], v[218:221], v[90:93]
	v_mfma_f32_16x16x32_bf16 v[78:81], v[134:137], v[242:245], v[78:81]
	v_mfma_f32_16x16x32_bf16 v[74:77], v[142:145], v[242:245], v[74:77]
	s_setprio 0
	s_setprio 1
	v_mfma_f32_16x16x32_bf16 v[118:121], v[156:159], v[172:175], v[118:121]
	v_mfma_f32_16x16x32_bf16 v[114:117], v[164:167], v[172:175], v[114:117]
	v_mfma_f32_16x16x32_bf16 v[102:105], v[156:159], v[206:209], v[102:105]
	v_mfma_f32_16x16x32_bf16 v[98:101], v[164:167], v[206:209], v[98:101]
	v_mfma_f32_16x16x32_bf16 v[86:89], v[156:159], v[214:217], v[86:89]
	v_mfma_f32_16x16x32_bf16 v[82:85], v[164:167], v[214:217], v[82:85]
	v_mfma_f32_16x16x32_bf16 v[70:73], v[156:159], v[222:225], v[70:73]
	v_mfma_f32_16x16x32_bf16 v[66:69], v[164:167], v[222:225], v[66:69]
	v_mfma_f32_16x16x32_bf16 v[118:121], v[160:163], v[202:205], v[118:121]
	v_mfma_f32_16x16x32_bf16 v[114:117], v[168:171], v[202:205], v[114:117]
	v_mfma_f32_16x16x32_bf16 v[102:105], v[160:163], v[210:213], v[102:105]
	v_mfma_f32_16x16x32_bf16 v[98:101], v[168:171], v[210:213], v[98:101]
	v_mfma_f32_16x16x32_bf16 v[86:89], v[160:163], v[218:221], v[86:89]
	v_mfma_f32_16x16x32_bf16 v[82:85], v[168:171], v[218:221], v[82:85]
	v_mfma_f32_16x16x32_bf16 v[70:73], v[160:163], v[242:245], v[70:73]
	v_mfma_f32_16x16x32_bf16 v[66:69], v[168:171], v[242:245], v[66:69]
	s_setprio 0
	s_barrier
	s_add_i32 m0, s46, 0xffffff80
	ds_read_b128 v[172:175], v179 offset:49152
	ds_read_b128 v[202:205], v179 offset:50176
	ds_read_b128 v[206:209], v179 offset:51200
	ds_read_b128 v[210:213], v179 offset:52224
	ds_read_b128 v[214:217], v179 offset:53248
	ds_read_b128 v[218:221], v179 offset:54272
	ds_read_b128 v[222:225], v179 offset:55296
	ds_read_b128 v[242:245], v179 offset:56320
	global_load_lds_dwordx4 v64, s[28:29] offset:128
	s_add_i32 m0, s47, 0xffffff80
	s_nop 0
	global_load_lds_dwordx4 v146, s[28:29] offset:128
	s_add_i32 m0, s50, 0xffffff80
	s_nop 0
	global_load_lds_dwordx4 v64, s[76:77] offset:128
	s_add_i32 m0, s51, 0xffffff80
	s_nop 0
	global_load_lds_dwordx4 v146, s[76:77] offset:128
	s_add_i32 m0, s48, 0xffffff80
	s_nop 0
	global_load_lds_dwordx4 v150, s[30:31] offset:128
	s_add_i32 m0, s49, 0xffffff80
	s_nop 0
	global_load_lds_dwordx4 v148, s[30:31] offset:128
	s_waitcnt vmcnt(8)
	s_waitcnt lgkmcnt(0)
	s_barrier
	s_setprio 1
	s_waitcnt lgkmcnt(0)
	v_mfma_f32_16x16x32_bf16 v[60:63], v[130:133], v[172:175], v[60:63]
	v_mfma_f32_16x16x32_bf16 v[56:59], v[138:141], v[172:175], v[56:59]
	v_mfma_f32_16x16x32_bf16 v[44:47], v[130:133], v[206:209], v[44:47]
	v_mfma_f32_16x16x32_bf16 v[40:43], v[138:141], v[206:209], v[40:43]
	v_mfma_f32_16x16x32_bf16 v[28:31], v[130:133], v[214:217], v[28:31]
	v_mfma_f32_16x16x32_bf16 v[24:27], v[138:141], v[214:217], v[24:27]
	v_mfma_f32_16x16x32_bf16 v[12:15], v[130:133], v[222:225], v[12:15]
	v_mfma_f32_16x16x32_bf16 v[8:11], v[138:141], v[222:225], v[8:11]
	v_mfma_f32_16x16x32_bf16 v[60:63], v[134:137], v[202:205], v[60:63]
	v_mfma_f32_16x16x32_bf16 v[56:59], v[142:145], v[202:205], v[56:59]
	v_mfma_f32_16x16x32_bf16 v[44:47], v[134:137], v[210:213], v[44:47]
	v_mfma_f32_16x16x32_bf16 v[40:43], v[142:145], v[210:213], v[40:43]
	v_mfma_f32_16x16x32_bf16 v[28:31], v[134:137], v[218:221], v[28:31]
	v_mfma_f32_16x16x32_bf16 v[24:27], v[142:145], v[218:221], v[24:27]
	v_mfma_f32_16x16x32_bf16 v[12:15], v[134:137], v[242:245], v[12:15]
	v_mfma_f32_16x16x32_bf16 v[8:11], v[142:145], v[242:245], v[8:11]
	s_setprio 0
	s_setprio 1
	v_mfma_f32_16x16x32_bf16 v[52:55], v[156:159], v[172:175], v[52:55]
	v_mfma_f32_16x16x32_bf16 v[48:51], v[164:167], v[172:175], v[48:51]
	v_mfma_f32_16x16x32_bf16 v[36:39], v[156:159], v[206:209], v[36:39]
	v_mfma_f32_16x16x32_bf16 v[32:35], v[164:167], v[206:209], v[32:35]
	v_mfma_f32_16x16x32_bf16 v[20:23], v[156:159], v[214:217], v[20:23]
	v_mfma_f32_16x16x32_bf16 v[16:19], v[164:167], v[214:217], v[16:19]
	v_mfma_f32_16x16x32_bf16 v[4:7], v[156:159], v[222:225], v[4:7]
	v_mfma_f32_16x16x32_bf16 v[0:3], v[164:167], v[222:225], v[0:3]
	v_mfma_f32_16x16x32_bf16 v[52:55], v[160:163], v[202:205], v[52:55]
	v_mfma_f32_16x16x32_bf16 v[48:51], v[168:171], v[202:205], v[48:51]
	v_mfma_f32_16x16x32_bf16 v[36:39], v[160:163], v[210:213], v[36:39]
	v_mfma_f32_16x16x32_bf16 v[32:35], v[168:171], v[210:213], v[32:35]
	v_mfma_f32_16x16x32_bf16 v[20:23], v[160:163], v[218:221], v[20:23]
	v_mfma_f32_16x16x32_bf16 v[16:19], v[168:171], v[218:221], v[16:19]
	v_mfma_f32_16x16x32_bf16 v[4:7], v[160:163], v[242:245], v[4:7]
	v_mfma_f32_16x16x32_bf16 v[0:3], v[168:171], v[242:245], v[0:3]
	s_setprio 0
	s_barrier
	s_add_i32 s74, s74, 2
	s_add_u32 s10, s10, 0x100
	s_addc_u32 s11, s11, 0
	s_add_u32 s72, s72, 0x100
	s_addc_u32 s73, s73, 0
	s_cmp_gt_u32 s74, 29
	s_cbranch_scc0 .LBB0_323
	s_and_b64 vcc, exec, s[16:17]
	s_cbranch_vccz .LBB0_326
	s_barrier
.LBB0_326:
	s_lshl_b32 s1, s87, 8
	v_add_u32_e32 v170, s1, v178
	v_ashrrev_i32_e32 v171, 31, v170
	v_lshl_add_u64 v[130:131], v[170:171], 2, s[14:15]
	global_load_dword v132, v[130:131], off
	global_load_dword v133, v[130:131], off offset:64
	global_load_dword v134, v[130:131], off offset:128
	global_load_dword v135, v[130:131], off offset:192
	global_load_dword v136, v[130:131], off offset:512
	global_load_dword v137, v[130:131], off offset:576
	global_load_dword v138, v[130:131], off offset:640
	s_nop 0
	global_load_dword v130, v[130:131], off offset:704
	s_cmp_lt_i32 s88, 24
	s_cselect_b64 s[30:31], -1, 0
	s_lshl_b32 s21, s88, 8
	s_add_i32 s34, s21, 0xffffe800
	s_cmp_gt_i32 s88, 23
	s_cselect_b64 s[28:29], -1, 0
	s_and_b64 s[10:11], s[28:29], exec
	s_cselect_b32 s10, s34, s21
	s_and_b32 s21, s88, 7
	s_cmp_lt_i32 s88, 16
	v_or_b32_e32 v174, s10, v191
	s_cselect_b64 s[10:11], -1, 0
	s_cmp_gt_u32 s21, 1
	s_cselect_b64 s[34:35], -1, 0
	s_and_b64 s[10:11], s[10:11], s[34:35]
	s_mov_b64 s[34:35], -1
	v_readlane_b32 s91, v254, 63
	s_waitcnt vmcnt(0)
	v_fmamk_f32 v131, v132, 0x3a000000, v230
	v_cmp_gt_f32_e32 vcc, s82, v131
	v_mul_f32_e32 v132, 0x4b800000, v131
	v_fmamk_f32 v130, v130, 0x3a000000, v230
	v_cndmask_b32_e32 v131, v131, v132, vcc
	v_rsq_f32_e32 v131, v131
	s_nop 0
	v_mul_f32_e32 v132, 0x45800000, v131
	v_cndmask_b32_e32 v172, v131, v132, vcc
	v_fmamk_f32 v131, v133, 0x3a000000, v230
	v_cmp_gt_f32_e32 vcc, s82, v131
	v_mul_f32_e32 v132, 0x4b800000, v131
	s_nop 0
	v_cndmask_b32_e32 v131, v131, v132, vcc
	v_rsq_f32_e32 v131, v131
	s_nop 0
	v_mul_f32_e32 v132, 0x45800000, v131
	v_cndmask_b32_e32 v168, v131, v132, vcc
	v_fmamk_f32 v131, v134, 0x3a000000, v230
	v_cmp_gt_f32_e32 vcc, s82, v131
	v_mul_f32_e32 v132, 0x4b800000, v131
	s_nop 0
	v_cndmask_b32_e32 v131, v131, v132, vcc
	v_rsq_f32_e32 v131, v131
	s_nop 0
	v_mul_f32_e32 v132, 0x45800000, v131
	v_cndmask_b32_e32 v166, v131, v132, vcc
	v_fmamk_f32 v131, v135, 0x3a000000, v230
	v_cmp_gt_f32_e32 vcc, s82, v131
	v_mul_f32_e32 v132, 0x4b800000, v131
	s_nop 0
	v_cndmask_b32_e32 v131, v131, v132, vcc
	v_rsq_f32_e32 v131, v131
	s_nop 0
	v_mul_f32_e32 v132, 0x45800000, v131
	v_cndmask_b32_e32 v164, v131, v132, vcc
	v_fmamk_f32 v131, v136, 0x3a000000, v230
	v_cmp_gt_f32_e32 vcc, s82, v131
	v_mul_f32_e32 v132, 0x4b800000, v131
	s_nop 0
	v_cndmask_b32_e32 v131, v131, v132, vcc
	v_rsq_f32_e32 v131, v131
	s_nop 0
	v_mul_f32_e32 v132, 0x45800000, v131
	v_cndmask_b32_e32 v162, v131, v132, vcc
	v_fmamk_f32 v131, v137, 0x3a000000, v230
	v_cmp_gt_f32_e32 vcc, s82, v131
	v_mul_f32_e32 v132, 0x4b800000, v131
	s_nop 0
	v_cndmask_b32_e32 v131, v131, v132, vcc
	v_rsq_f32_e32 v131, v131
	s_nop 0
	v_mul_f32_e32 v132, 0x45800000, v131
	v_cndmask_b32_e32 v160, v131, v132, vcc
	v_fmamk_f32 v131, v138, 0x3a000000, v230
	v_cmp_gt_f32_e32 vcc, s82, v131
	v_mul_f32_e32 v132, 0x4b800000, v131
	s_nop 0
	v_cndmask_b32_e32 v131, v131, v132, vcc
	v_rsq_f32_e32 v131, v131
	s_nop 0
	v_mul_f32_e32 v132, 0x45800000, v131
	v_cndmask_b32_e32 v158, v131, v132, vcc
	v_cmp_gt_f32_e32 vcc, s82, v130
	v_mul_f32_e32 v131, 0x4b800000, v130
	s_nop 0
	v_cndmask_b32_e32 v130, v130, v131, vcc
	v_rsq_f32_e32 v130, v130
	s_nop 0
	v_mul_f32_e32 v131, 0x45800000, v130
	v_cndmask_b32_e32 v156, v130, v131, vcc
	s_and_b64 vcc, exec, s[10:11]
	s_cbranch_vccnz .LBB0_392
	v_cndmask_b32_e64 v130, 0, 1, s[30:31]
	v_pk_mul_f32 v[134:135], v[128:129], v[172:173] op_sel_hi:[1,0]
	v_pk_mul_f32 v[136:137], v[126:127], v[172:173] op_sel_hi:[1,0]
	v_pk_mul_f32 v[138:139], v[124:125], v[172:173] op_sel_hi:[1,0]
	v_pk_mul_f32 v[140:141], v[122:123], v[172:173] op_sel_hi:[1,0]
	v_cmp_ne_u32_e64 s[10:11], 1, v130
	s_andn2_b64 vcc, exec, s[30:31]
	s_mov_b64 s[30:31], -1
	s_cbranch_vccnz .LBB0_329
	s_mov_b64 s[30:31], 0

	.amdhsa_kernel _Z10hybrid_fwd4Args
		.amdhsa_group_segment_fixed_size 143360
		.amdhsa_private_segment_fixed_size 0
		.amdhsa_kernarg_size 368
		.amdhsa_user_sgpr_count 2
		.amdhsa_user_sgpr_dispatch_ptr 0
		.amdhsa_user_sgpr_queue_ptr 0
		.amdhsa_user_sgpr_kernarg_segment_ptr 1
		.amdhsa_user_sgpr_dispatch_id 0
		.amdhsa_user_sgpr_kernarg_preload_length 0
		.amdhsa_user_sgpr_kernarg_preload_offset 0
		.amdhsa_user_sgpr_private_segment_size 0
		.amdhsa_uses_dynamic_stack 0
		.amdhsa_enable_private_segment 0
		.amdhsa_system_sgpr_workgroup_id_x 1
		.amdhsa_system_sgpr_workgroup_id_y 0
		.amdhsa_system_sgpr_workgroup_id_z 0
		.amdhsa_system_sgpr_workgroup_info 0
		.amdhsa_system_vgpr_workitem_id 2
		.amdhsa_next_free_vgpr 256
		.amdhsa_next_free_sgpr 100
		.amdhsa_accum_offset 256
		.amdhsa_reserve_vcc 1
		.amdhsa_float_round_mode_32 0
		.amdhsa_float_round_mode_16_64 0
		.amdhsa_float_denorm_mode_32 3
		.amdhsa_float_denorm_mode_16_64 3
		.amdhsa_dx10_clamp 1
		.amdhsa_ieee_mode 1
		.amdhsa_fp16_overflow 0
		.amdhsa_tg_split 0
		.amdhsa_exception_fp_ieee_invalid_op 0
		.amdhsa_exception_fp_denorm_src 0
		.amdhsa_exception_fp_ieee_div_zero 0
		.amdhsa_exception_fp_ieee_overflow 0
		.amdhsa_exception_fp_ieee_underflow 0
		.amdhsa_exception_fp_ieee_inexact 0
		.amdhsa_exception_int_div_zero 0
	.end_amdhsa_kernel

.Lfunc_end0:
	.size	_Z10hybrid_fwd4Args, .Lfunc_end0-_Z10hybrid_fwd4Args
	.set _Z10hybrid_fwd4Args.num_vgpr, 256
	.set _Z10hybrid_fwd4Args.num_agpr, 0
	.set _Z10hybrid_fwd4Args.numbered_sgpr, 100
	.set _Z10hybrid_fwd4Args.num_named_barrier, 0
	.set _Z10hybrid_fwd4Args.private_seg_size, 0
	.set _Z10hybrid_fwd4Args.uses_vcc, 1
	.set _Z10hybrid_fwd4Args.uses_flat_scratch, 0
	.set _Z10hybrid_fwd4Args.has_dyn_sized_stack, 0
	.set _Z10hybrid_fwd4Args.has_recursion, 0
	.set _Z10hybrid_fwd4Args.has_indirect_call, 0

amdhsa.kernels:
  - .agpr_count:     0
    .args:
      - .offset:         0
        .size:           112
        .value_kind:     by_value
      - .offset:         112
        .size:           4
        .value_kind:     hidden_block_count_x
      - .offset:         116
        .size:           4
        .value_kind:     hidden_block_count_y
      - .offset:         120
        .size:           4
        .value_kind:     hidden_block_count_z
      - .offset:         124
        .size:           2
        .value_kind:     hidden_group_size_x
      - .offset:         126
        .size:           2
        .value_kind:     hidden_group_size_y
      - .offset:         128
        .size:           2
        .value_kind:     hidden_group_size_z
      - .offset:         130
        .size:           2
        .value_kind:     hidden_remainder_x
      - .offset:         132
        .size:           2
        .value_kind:     hidden_remainder_y
      - .offset:         134
        .size:           2
        .value_kind:     hidden_remainder_z
      - .offset:         152
        .size:           8
        .value_kind:     hidden_global_offset_x
      - .offset:         160
        .size:           8
        .value_kind:     hidden_global_offset_y
      - .offset:         168
        .size:           8
        .value_kind:     hidden_global_offset_z
      - .offset:         176
        .size:           2
        .value_kind:     hidden_grid_dims
      - .offset:         200
        .size:           8
        .value_kind:     hidden_multigrid_sync_arg
    .group_segment_fixed_size: 143360
    .kernarg_segment_align: 8
    .kernarg_segment_size: 368
    .language:       OpenCL C
    .language_version:
      - 2
      - 0
    .max_flat_workgroup_size: 512
    .name:           _Z10hybrid_fwd4Args
    .private_segment_fixed_size: 0
    .sgpr_count:     106
    .sgpr_spill_count: 93
    .symbol:         _Z10hybrid_fwd4Args.kd
    .uniform_work_group_size: 1
    .uses_dynamic_stack: false
    .vgpr_count:     256
    .vgpr_spill_count: 0
    .wavefront_size: 64
  - .agpr_count:     0
    .args:
      - .address_space:  global
        .offset:         0
        .size:           8
        .value_kind:     global_buffer
      - .offset:         8
        .size:           4
        .value_kind:     by_value
      - .offset:         12
        .size:           4
        .value_kind:     by_value
      - .offset:         16
        .size:           4
        .value_kind:     hidden_block_count_x
      - .offset:         20
        .size:           4
        .value_kind:     hidden_block_count_y
      - .offset:         24
        .size:           4
        .value_kind:     hidden_block_count_z
      - .offset:         28
        .size:           2
        .value_kind:     hidden_group_size_x
      - .offset:         30
        .size:           2
        .value_kind:     hidden_group_size_y
      - .offset:         32
        .size:           2
        .value_kind:     hidden_group_size_z
      - .offset:         34
        .size:           2
        .value_kind:     hidden_remainder_x
      - .offset:         36
        .size:           2
        .value_kind:     hidden_remainder_y
      - .offset:         38
        .size:           2
        .value_kind:     hidden_remainder_z
      - .offset:         56
        .size:           8
        .value_kind:     hidden_global_offset_x
      - .offset:         64
        .size:           8
        .value_kind:     hidden_global_offset_y
      - .offset:         72
        .size:           8
        .value_kind:     hidden_global_offset_z
      - .offset:         80
        .size:           2
        .value_kind:     hidden_grid_dims
    .group_segment_fixed_size: 0
    .kernarg_segment_align: 8
    .kernarg_segment_size: 272
    .language:       OpenCL C
    .language_version:
      - 2
      - 0
    .max_flat_workgroup_size: 1024
    .name:           _Z10fill_constPfif
    .private_segment_fixed_size: 0
    .sgpr_count:     16
    .sgpr_spill_count: 0
    .symbol:         _Z10fill_constPfif.kd
    .uniform_work_group_size: 1
    .uses_dynamic_stack: false
    .vgpr_count:     6
    .vgpr_spill_count: 0
    .wavefront_size: 64
